# attention inner loop rewritten: software-pipelined 32-key steps, QK(next) MFMAs interleaved with exp/cvt/rowsum of current, V LDS layout permuted for b128 reads, 3-deep V ring
# speedup vs baseline: 1.0280x; 1.0280x over previous
; __device__ __forceinline__ int opaque_tid() { int t = threadIdx.x; asm volatile("" : "+v"(t)); return t; }
; __device__ __forceinline__ void attn_phase(const Params& p, LAS unsigned char* lds, int G) {
;     ...
;     const int tid = opaque_tid(), lane = tid & 63, wave = __builtin_amdgcn_readfirstlane(tid >> 6), l32 = lane & 31, hi = lane >> 5;
;     const bf16_t* QRAW = (const bf16_t*)(ws + WS_QRAW); const bf16_t* KF = (const bf16_t*)(ws + WS_KF); const bf16_t* VT = (const bf16_t*)(ws + WS_VT);
;     const float* COS = (const float*)(ws + WS_COS); const float* SIN = (const float*)(ws + WS_SIN);
;     bf16_t* Y = (bf16_t*)(ws + WS_Y);
;     const int kr0 = tid / 12, kc0 = tid - kr0 * 12;
;     const int kr1 = (tid + 512) / 12, kc1 = (tid + 512) - kr1 * 12;
;     const int kr2 = (tid + 1024) / 12, kc2 = (tid + 1024) - kr2 * 12;
;     const int vr0 = tid >> 4, vc0 = tid & 15;
;     float negsb;
;     {
;         float gq = fmaxf(fabsf(p.in[15][lane]), fabsf(p.in[15][64 + l32])), gk = fmaxf(fabsf(p.in[16][lane]), fabsf(p.in[16][64 + l32]));
; #pragma unroll
;         for (int o = 1; o < 64; o <<= 1) { gq = fmaxf(gq, __shfl_xor(gq, o)); gk = fmaxf(gk, __shfl_xor(gk, o)); }
;         negsb = -(96.f * gq * gk * QSCALE);
;     }
;     f32x16 negv;
; #pragma unroll
;     for (int e = 0; e < 16; ++e) negv[e] = negsb;
;     asm volatile("" : "+v"(negv));
.LBB0_628:
	s_cmp_lt_i32 s94, 7
	s_cselect_b64 s[4:5], -1, 0
	s_and_b64 s[28:29], s[4:5], s[0:1]
	s_andn2_b64 vcc, exec, s[28:29]
	s_cbranch_vccnz .LBB0_660
	s_waitcnt vmcnt(0)
	v_mov_b32_e32 v16, v166
	v_mbcnt_lo_u32_b32 v4, -1, 0
	v_and_b32_e32 v17, 63, v16
	v_and_b32_e32 v170, 31, v16
	v_lshlrev_b32_e32 v0, 2, v17
	v_lshlrev_b32_e32 v171, 2, v170
	s_waitcnt lgkmcnt(0)
	global_load_dword v1, v171, s[70:71] offset:256
	global_load_dword v2, v0, s[70:71]
	global_load_dword v3, v171, s[72:73] offset:256
	s_nop 0
	global_load_dword v0, v0, s[72:73]
	v_mbcnt_hi_u32_b32 v4, -1, v4
	v_and_b32_e32 v5, 64, v4
	v_xor_b32_e32 v6, 1, v4
	v_add_u32_e32 v5, 64, v5
	v_cmp_lt_i32_e32 vcc, v6, v5
	v_xor_b32_e32 v7, 2, v4
	v_xor_b32_e32 v8, 4, v4
	v_cndmask_b32_e32 v6, v4, v6, vcc
	v_lshlrev_b32_e32 v167, 2, v6
	v_cmp_lt_i32_e32 vcc, v7, v5
	v_xor_b32_e32 v9, 8, v4
	v_xor_b32_e32 v10, 16, v4
	v_cndmask_b32_e32 v6, v4, v7, vcc
	v_lshlrev_b32_e32 v168, 2, v6
	v_cmp_lt_i32_e32 vcc, v8, v5
	v_xor_b32_e32 v11, 32, v4
	s_cmpk_gt_i32 s2, 0x7ff
	v_cndmask_b32_e32 v6, v4, v8, vcc
	v_lshlrev_b32_e32 v6, 2, v6
	v_cmp_lt_i32_e32 vcc, v9, v5
	s_mov_b32 s31, 0
	v_readfirstlane_b32 s0, v16
	s_waitcnt vmcnt(3)
	v_max_f32_e64 v1, |v1|, |v1|
	s_waitcnt vmcnt(2)
	v_max_f32_e64 v2, |v2|, |v2|
	s_waitcnt vmcnt(1)
	v_max_f32_e64 v3, |v3|, |v3|
	s_waitcnt vmcnt(0)
	v_max_f32_e64 v0, |v0|, |v0|
	v_max_f32_e32 v1, v2, v1
	v_max_f32_e32 v0, v0, v3
	ds_bpermute_b32 v2, v167, v1
	ds_bpermute_b32 v3, v167, v0
	s_waitcnt lgkmcnt(1)
	v_max_f32_e32 v2, v2, v2
	s_waitcnt lgkmcnt(0)
	v_max_f32_e32 v3, v3, v3
	v_max_f32_e32 v1, v1, v2
	v_max_f32_e32 v0, v0, v3
	ds_bpermute_b32 v2, v168, v1
	ds_bpermute_b32 v3, v168, v0
	s_waitcnt lgkmcnt(1)
	v_max_f32_e32 v2, v2, v2
	s_waitcnt lgkmcnt(0)
	v_max_f32_e32 v3, v3, v3
	v_max_f32_e32 v1, v1, v2
	v_max_f32_e32 v0, v0, v3
	ds_bpermute_b32 v2, v6, v1
	ds_bpermute_b32 v3, v6, v0
	v_cndmask_b32_e32 v6, v4, v9, vcc
	v_lshlrev_b32_e32 v6, 2, v6
	v_cmp_lt_i32_e32 vcc, v10, v5
	s_waitcnt lgkmcnt(1)
	v_max_f32_e32 v2, v2, v2
	s_waitcnt lgkmcnt(0)
	v_max_f32_e32 v3, v3, v3
	v_max_f32_e32 v1, v1, v2
	v_max_f32_e32 v0, v0, v3
	ds_bpermute_b32 v2, v6, v1
	ds_bpermute_b32 v3, v6, v0
	v_cndmask_b32_e32 v6, v4, v10, vcc
	v_lshlrev_b32_e32 v6, 2, v6
	v_cmp_lt_i32_e32 vcc, v11, v5
	s_waitcnt lgkmcnt(1)
	v_max_f32_e32 v2, v2, v2
	s_waitcnt lgkmcnt(0)
	v_max_f32_e32 v3, v3, v3
	v_max_f32_e32 v1, v1, v2
	v_max_f32_e32 v0, v0, v3
	ds_bpermute_b32 v2, v6, v1
	ds_bpermute_b32 v3, v6, v0
	v_cndmask_b32_e32 v4, v4, v11, vcc
	v_lshlrev_b32_e32 v169, 2, v4
	s_waitcnt lgkmcnt(1)
	v_max_f32_e32 v2, v2, v2
	s_waitcnt lgkmcnt(0)
	v_max_f32_e32 v3, v3, v3
	v_max_f32_e32 v1, v1, v2
	v_max_f32_e32 v0, v0, v3
	ds_bpermute_b32 v2, v169, v1
	ds_bpermute_b32 v3, v169, v0
	s_waitcnt lgkmcnt(1)
	v_max_f32_e32 v2, v2, v2
	s_waitcnt lgkmcnt(0)
	v_max_f32_e32 v3, v3, v3
	v_max_f32_e32 v1, v1, v2
	v_max_f32_e32 v0, v0, v3
	v_mul_f32_e32 v1, 0x42c00000, v1
	v_mul_f32_e32 v0, v0, v1
	v_mul_f32_e32 v0, 0xbe16c740, v0
	v_mov_b32_e32 v1, v0
	v_mov_b32_e32 v2, v0
	v_mov_b32_e32 v3, v0
	v_mov_b32_e32 v4, v0
	v_mov_b32_e32 v5, v0
	v_mov_b32_e32 v6, v0
	v_mov_b32_e32 v7, v0
	v_mov_b32_e32 v8, v0
	v_mov_b32_e32 v9, v0
	v_mov_b32_e32 v10, v0
	v_mov_b32_e32 v11, v0
	v_mov_b32_e32 v12, v0
	v_mov_b32_e32 v13, v0
	v_mov_b32_e32 v14, v0
	v_mov_b32_e32 v15, v0
	s_cbranch_scc1 .LBB0_649
; __device__ __forceinline__ void attn_phase(const Params& p, LAS unsigned char* lds, int G) {
;     ...
;     const bf16_t* QRAW = (const bf16_t*)(ws + WS_QRAW); const bf16_t* KF = (const bf16_t*)(ws + WS_KF); const bf16_t* VT = (const bf16_t*)(ws + WS_VT);
;     const float* COS = (const float*)(ws + WS_COS); const float* SIN = (const float*)(ws + WS_SIN);
;     bf16_t* Y = (bf16_t*)(ws + WS_Y);
;     const int kr0 = tid / 12, kc0 = tid - kr0 * 12;
;     const int kr1 = (tid + 512) / 12, kc1 = (tid + 512) - kr1 * 12;
;     const int kr2 = (tid + 1024) / 12, kc2 = (tid + 1024) - kr2 * 12;
;     const int vr0 = tid >> 4, vc0 = tid & 15;
	v_add_u32_e32 v18, 0x200, v16
	s_mov_b32 s1, 0x2aaaaaab
	v_mul_hi_i32 v19, v18, s1
	v_lshrrev_b32_e32 v20, 31, v19
	v_ashrrev_i32_e32 v19, 1, v19
	v_add_u32_e32 v30, v19, v20
	v_mad_u64_u32 v[18:19], s[10:11], v30, -12, v[18:19]
	v_add_u32_e32 v20, 0x400, v16
	v_mul_hi_i32 v19, v20, s1
	v_lshrrev_b32_e32 v21, 31, v19
	v_ashrrev_i32_e32 v19, 1, v19
	s_add_u32 s4, s92, 0x36000000
	v_add_u32_e32 v19, v19, v21
	s_addc_u32 s5, s93, 0
	v_mad_u64_u32 v[20:21], s[10:11], v19, -12, v[20:21]
	s_add_u32 s6, s92, 0x3c000000
	v_mul_hi_i32 v21, v16, s1
	s_addc_u32 s7, s93, 0
	v_lshrrev_b32_e32 v22, 31, v21
	v_ashrrev_i32_e32 v21, 1, v21
	s_add_u32 s34, s92, 0x22000000
	v_add_u32_e32 v31, v21, v22
	s_addc_u32 s35, s93, 0
	v_mad_u64_u32 v[22:23], s[10:11], v31, -12, v[16:17]
	s_add_u32 s8, s92, 0x3380000
	v_ashrrev_i32_e32 v24, 4, v16
	s_movk_i32 s11, 0x60
	s_addc_u32 s9, s93, 0
	s_ashr_i32 s10, s0, 1
	v_mad_i64_i32 v[126:127], s[0:1], v31, s11, 0
	v_mad_i64_i32 v[130:131], s[0:1], v30, s11, 0
	v_mad_i64_i32 v[134:135], s[0:1], v19, s11, 0
	v_ashrrev_i32_e32 v25, 31, v24
	v_mov_b32_e32 v125, 0
	v_lshlrev_b64 v[138:139], 12, v[24:25]
	s_mov_b64 s[0:1], 0x20000
	v_and_b32_e32 v124, 32, v17
	v_lshl_add_u64 v[140:141], v[138:139], 0, s[0:1]
	v_lshl_add_u64 v[28:29], s[92:93], 0, v[124:125]
	s_mov_b64 s[0:1], 0x2a00000
	v_lshl_add_u64 v[142:143], v[28:29], 0, s[0:1]
	s_mov_b64 s[0:1], 0x2e00000
	v_lshl_add_u64 v[144:145], v[28:29], 0, s[0:1]
	s_movk_i32 s0, 0x108
	v_lshrrev_b32_e32 v21, 5, v17
	v_lshlrev_b32_e32 v128, 3, v22
	v_mul_lo_u32 v23, v24, s0
	s_movk_i32 s0, 0xd0
	v_ashrrev_i32_e32 v129, 31, v128
	v_lshlrev_b32_e32 v132, 3, v18
	v_lshlrev_b32_e32 v136, 3, v20
	v_lshlrev_b32_e32 v26, 3, v21
	v_lshlrev_b32_e32 v176, 4, v18
	v_lshlrev_b32_e32 v178, 4, v20
	v_mad_u32_u24 v18, v170, s0, 0
	v_mul_u32_u24_e32 v20, 56, v170
	v_lshl_add_u32 v179, v21, 4, v18
	v_add3_u32 v180, v18, v20, v26
	v_lshlrev_b32_e32 v18, 2, v21
	v_lshlrev_b64 v[20:21], 1, v[128:129]
	s_movk_i32 s11, 0xc0
	v_mul_lo_u32 v173, v31, s0
	v_mul_lo_u32 v175, v30, s0
	v_mul_lo_u32 v177, v19, s0
	v_mad_i64_i32 v[20:21], s[0:1], v31, s11, v[20:21]
	v_ashrrev_i32_e32 v133, 31, v132
	v_lshl_add_u64 v[20:21], s[92:93], 0, v[20:21]
	s_mov_b64 s[0:1], 0x36006000
	v_lshl_add_u64 v[148:149], v[20:21], 0, s[0:1]
	v_lshlrev_b64 v[20:21], 1, v[132:133]
	v_mad_i64_i32 v[20:21], s[14:15], v30, s11, v[20:21]
	v_ashrrev_i32_e32 v137, 31, v136
	v_lshl_add_u64 v[20:21], s[92:93], 0, v[20:21]
	v_and_b32_e32 v27, 15, v16
	v_lshl_add_u64 v[150:151], v[20:21], 0, s[0:1]
	v_lshlrev_b64 v[20:21], 1, v[136:137]
	v_lshlrev_b32_e32 v24, 4, v27
	v_mad_i64_i32 v[20:21], s[14:15], v19, s11, v[20:21]
	v_lshlrev_b32_e32 v16, 3, v27
	v_add3_u32 v172, 0, v23, v24
	v_add_u32_e32 v23, 0, v173
	v_lshlrev_b32_e32 v174, 4, v22
	v_add_u32_e32 v22, 0, v175
	v_add_u32_e32 v24, 0, v177
	v_lshl_add_u64 v[20:21], s[92:93], 0, v[20:21]
	s_andn2_b32 s10, s10, 31
	v_add_u32_e32 v181, 0x3400, v179
	v_cmp_gt_u32_e64 s[38:39], 32, v17
	v_lshl_add_u64 v[146:147], s[70:71], 0, v[124:125]
	v_lshl_add_u64 v[152:153], v[20:21], 0, s[0:1]
	v_lshlrev_b32_e32 v124, 1, v16
	v_lshlrev_b32_e32 v154, 1, v26
	v_mov_b32_e32 v182, 0x358637bd
	v_mov_b32_e32 v183, 0x260
	s_mov_b32 s11, 0x3e16c740
	v_add_u32_e32 v184, v23, v174
	v_add_u32_e32 v185, v22, v176
	v_add_u32_e32 v186, v24, v178
	s_mov_b64 s[36:37], 0x6000
	v_lshlrev_b32_e32 v156, 1, v18
	v_mov_b32_e32 v187, 0xc0000
	v_mov_b32_e32 v188, 0x600
	s_mov_b32 s44, s2
	v_and_b32_e32 v249, 31, v166
	v_mul_u32_u24_e32 v249, 0x110, v249
	v_bfe_u32 v251, v166, 5, 1
	v_lshl_add_u32 v249, v251, 4, v249
	v_bfe_u32 v250, v166, 4, 5
	v_mul_u32_u24_e32 v250, 0x110, v250
	v_bfe_u32 v251, v166, 1, 3
	v_lshl_add_u32 v250, v251, 5, v250
	v_and_b32_e32 v251, 1, v166
	v_lshl_add_u32 v250, v251, 3, v250
	s_branch .LBB0_632

; __device__ __forceinline__ float sq4(f32x4 a) { return (a.x * a.x + a.y * a.y) + (a.z * a.z + a.w * a.w); }
; __device__ __forceinline__ void attn_phase(const Params& p, LAS unsigned char* lds, int G) {
;     ...
;         const int kk = it >> 8, cc = it & 255, bh = cc >> 1, set = cc & 1;
;         const int qt = set ? (14 - 2 * kk + (kk & 1)) : (15 - 2 * kk - (kk & 1));
;         const int q0 = qt * 256 + 32 * wave, lim = q0 >> 6, nkt = 4 * qt + 4;
;         const bf16_t* kbase = KF + (size_t)bh * SEQ * 96; const bf16_t* vbase = VT + (size_t)bh * 64 * SEQ;
;         u32x4 rk0, rk1, rk2, rv0, rv1;
;         ATT_LOAD(0);
;         bf16x8 qf[6];
;         {
;             const size_t qrow = (size_t)(bh >> 3) * SEQ + q0 + l32;
;             const bf16_t* qp = QRAW + qrow * 768 + (bh & 7) * 96 + 8 * hi;
;             u32x4 qr[6];
; #pragma unroll
;             for (int ks = 0; ks < 6; ++ks) qr[ks] = *(const u32x4*)(qp + 16 * ks);
;             const f32x4 c0 = *(const f32x4*)(COS + qrow * 16 + 8 * hi), c1 = *(const f32x4*)(COS + qrow * 16 + 8 * hi + 4);
;             const f32x4 n0 = *(const f32x4*)(SIN + qrow * 16 + 8 * hi), n1 = *(const f32x4*)(SIN + qrow * 16 + 8 * hi + 4);
;             f32x4 xa[6], xb[6]; float ss = 0.f;
; #pragma unroll
;             for (int ks = 0; ks < 6; ++ks) { xa[ks] = (f32x4){bflo(qr[ks].x), bfhi(qr[ks].x), bflo(qr[ks].y), bfhi(qr[ks].y)}; xb[ks] = (f32x4){bflo(qr[ks].z), bfhi(qr[ks].z), bflo(qr[ks].w), bfhi(qr[ks].w)};
;                 ss += sq4(xa[ks]) + sq4(xb[ks]); }
;             ss += __shfl_xor(ss, 32);
.LBB0_636:
	s_bfe_u32 s15, s44, 0x70001
	v_mad_u64_u32 v[160:161], s[0:1], s15, v187, v[148:149]
	v_mad_u64_u32 v[162:163], s[0:1], s15, v187, v[150:151]
	v_mad_u64_u32 v[164:165], s[0:1], s15, v187, v[152:153]
	s_lshl_b32 s0, s14, 8
	s_add_i32 s40, s0, s10
	s_lshl_b32 s49, s14, 2
	s_mul_i32 s0, s15, 0xc0000
	s_add_u32 s0, s4, s0
	s_addc_u32 s1, s5, 0
	v_lshl_add_u64 v[16:17], v[126:127], 1, s[0:1]
	v_lshl_add_u64 v[16:17], v[128:129], 1, v[16:17]
	global_load_dwordx4 v[80:83], v[16:17], off
	v_lshl_add_u64 v[16:17], v[130:131], 1, s[0:1]
	s_lshl_b32 s14, s15, 19
	v_lshl_add_u64 v[16:17], v[132:133], 1, v[16:17]
	s_add_u32 s42, s6, s14
	global_load_dwordx4 v[84:87], v[16:17], off
	v_lshl_add_u64 v[16:17], v[134:135], 1, s[0:1]
	s_addc_u32 s43, s7, 0
	v_lshl_add_u64 v[16:17], v[136:137], 1, v[16:17]
	global_load_dwordx4 v[88:91], v[16:17], off
	v_lshl_add_u64 v[16:17], v[138:139], 1, s[42:43]
	v_lshl_add_u64 v[16:17], v[16:17], 0, v[124:125]
	s_lshl_b32 s0, s44, 8
	global_load_dwordx4 v[92:95], v[16:17], off
	v_lshl_add_u64 v[16:17], v[140:141], 1, s[42:43]
	s_and_b32 s45, s0, 0xf000
	s_ashr_i32 s41, s40, 31
	v_lshl_add_u64 v[16:17], v[16:17], 0, v[124:125]
	s_add_u32 s0, s40, s45
	global_load_dwordx4 v[96:99], v[16:17], off
	v_or_b32_e32 v158, s0, v170
	v_mov_b64_e32 v[16:17], s[34:35]
	s_movk_i32 s0, 0x600
	s_addc_u32 s14, s41, 0
	v_mad_u64_u32 v[16:17], s[0:1], v158, s0, v[16:17]
	s_bfe_u32 s46, s44, 0x30001
	v_mad_i32_i24 v17, s14, v188, v17
	s_mul_i32 s30, s46, 0xc0
	v_lshl_add_u64 v[16:17], v[16:17], 0, s[30:31]
	v_mov_b32_e32 v155, v125
	v_lshl_add_u64 v[16:17], v[16:17], 0, v[154:155]
	global_load_dwordx4 v[44:47], v[16:17], off
	global_load_dwordx4 v[48:51], v[16:17], off offset:32
	global_load_dwordx4 v[52:55], v[16:17], off offset:64
	global_load_dwordx4 v[40:43], v[16:17], off offset:96
	global_load_dwordx4 v[32:35], v[16:17], off offset:128
	global_load_dwordx4 v[36:39], v[16:17], off offset:160
	s_mov_b32 s0, 0xf800000
	v_mov_b32_e32 v159, s14
	v_lshlrev_b64 v[20:21], 6, v[158:159]
	v_lshl_add_u64 v[22:23], v[142:143], 0, v[20:21]
	v_lshl_add_u64 v[28:29], v[144:145], 0, v[20:21]
	global_load_dwordx4 v[16:19], v[22:23], off offset:16
	global_load_dwordx4 v[24:27], v[22:23], off
	s_nop 0
	global_load_dwordx4 v[20:23], v[28:29], off offset:16
	s_nop 0
	global_load_dwordx4 v[28:31], v[28:29], off
	s_add_i32 s49, s49, 4
	s_ashr_i32 s47, s40, 6
	s_mov_b32 s48, 0
	s_lshr_b32 s14, s49, 1
	v_mov_b32_e32 v155, 0
	s_movk_i32 s30, 0x80
	s_mov_b32 s16, 0
	s_waitcnt vmcnt(9)
	v_and_b32_e32 v68, 0xffff0000, v44
	s_waitcnt vmcnt(8)
	v_and_b32_e32 v69, 0xffff0000, v48
	v_and_b32_e32 v73, 0xffff0000, v49
	v_and_b32_e32 v72, 0xffff0000, v45
	v_lshlrev_b32_e32 v67, 16, v48
	v_lshlrev_b32_e32 v66, 16, v44
	v_lshlrev_b32_e32 v71, 16, v49
	v_lshlrev_b32_e32 v70, 16, v45
	v_lshlrev_b32_e32 v106, 16, v46
	v_and_b32_e32 v108, 0xffff0000, v46
	v_lshlrev_b32_e32 v110, 16, v47
	v_and_b32_e32 v112, 0xffff0000, v47
	v_pk_mul_f32 v[44:45], v[68:69], v[68:69]
	v_pk_mul_f32 v[46:47], v[72:73], v[72:73]
	v_and_b32_e32 v109, 0xffff0000, v50
	v_and_b32_e32 v113, 0xffff0000, v51
	v_pk_fma_f32 v[44:45], v[66:67], v[66:67], v[44:45]
	v_pk_fma_f32 v[46:47], v[70:71], v[70:71], v[46:47]
	v_lshlrev_b32_e32 v107, 16, v50
	v_lshlrev_b32_e32 v111, 16, v51
	v_pk_add_f32 v[44:45], v[44:45], v[46:47]
	v_pk_mul_f32 v[46:47], v[108:109], v[108:109]
	v_pk_mul_f32 v[48:49], v[112:113], v[112:113]
	v_pk_fma_f32 v[46:47], v[106:107], v[106:107], v[46:47]
	v_pk_fma_f32 v[48:49], v[110:111], v[110:111], v[48:49]
	s_waitcnt vmcnt(7)
	v_and_b32_e32 v101, 0xffff0000, v54
	v_pk_add_f32 v[46:47], v[46:47], v[48:49]
	v_and_b32_e32 v100, 0xffff0000, v52
	v_and_b32_e32 v105, 0xffff0000, v55
	v_and_b32_e32 v104, 0xffff0000, v53
	v_pk_add_f32 v[48:49], v[44:45], v[46:47]
	v_lshlrev_b32_e32 v79, 16, v54
	v_lshlrev_b32_e32 v78, 16, v52
	v_lshlrev_b32_e32 v103, 16, v55
	v_lshlrev_b32_e32 v102, 16, v53
	v_pk_mul_f32 v[44:45], v[100:101], v[100:101]
	v_pk_mul_f32 v[46:47], v[104:105], v[104:105]
	v_pk_fma_f32 v[44:45], v[78:79], v[78:79], v[44:45]
	v_pk_fma_f32 v[46:47], v[102:103], v[102:103], v[46:47]
	s_waitcnt vmcnt(6)
	v_and_b32_e32 v65, 0xffff0000, v41
	v_and_b32_e32 v64, 0xffff0000, v40
	v_pk_add_f32 v[50:51], v[44:45], v[46:47]
	v_lshlrev_b32_e32 v63, 16, v41
	v_lshlrev_b32_e32 v62, 16, v40
	v_pk_mul_f32 v[40:41], v[64:65], v[64:65]
	v_and_b32_e32 v77, 0xffff0000, v43
	v_and_b32_e32 v76, 0xffff0000, v42
	s_waitcnt vmcnt(4)
	v_lshlrev_b32_e32 v46, 16, v36
	v_pk_fma_f32 v[52:53], v[62:63], v[62:63], v[40:41]
	v_lshlrev_b32_e32 v75, 16, v43
	v_lshlrev_b32_e32 v74, 16, v42
	v_pk_mul_f32 v[40:41], v[76:77], v[76:77]
	v_and_b32_e32 v47, 0xffff0000, v36
	v_lshlrev_b32_e32 v44, 16, v37
	v_and_b32_e32 v45, 0xffff0000, v37
	v_lshlrev_b32_e32 v42, 16, v38
	v_and_b32_e32 v43, 0xffff0000, v38
	v_mul_f32_e32 v38, v46, v46
	v_pk_add_f32 v[36:37], v[48:49], v[48:49] op_sel:[0,1] op_sel_hi:[1,0]
	v_pk_fma_f32 v[54:55], v[74:75], v[74:75], v[40:41]
	v_lshlrev_b32_e32 v40, 16, v39
	v_and_b32_e32 v41, 0xffff0000, v39
	v_mul_f32_e32 v56, v47, v47
	v_mov_b32_e32 v37, v38
	v_pk_add_f32 v[38:39], v[50:51], v[50:51] op_sel:[0,1] op_sel_hi:[1,0]
	v_mul_f32_e32 v57, v44, v44
	v_mov_b32_e32 v39, v56
	v_mul_f32_e32 v114, v45, v45
	v_pk_add_f32 v[36:37], v[36:37], v[38:39]
	v_pk_add_f32 v[38:39], v[52:53], v[52:53] op_sel:[0,1] op_sel_hi:[1,0]
	v_pk_add_f32 v[48:49], v[54:55], v[54:55] op_sel:[0,1] op_sel_hi:[1,0]
	v_mov_b32_e32 v39, v57
	v_mov_b32_e32 v49, v114
	v_and_b32_e32 v59, 0xffff0000, v32
	v_and_b32_e32 v61, 0xffff0000, v33
	v_pk_add_f32 v[38:39], v[38:39], v[48:49]
	v_lshlrev_b32_e32 v58, 16, v32
	v_lshlrev_b32_e32 v60, 16, v33
	v_pk_add_f32 v[36:37], v[36:37], v[38:39]
	v_mul_f32_e32 v38, v59, v59
	v_mul_f32_e32 v48, v61, v61
	v_mul_f32_e32 v115, v42, v42
	v_mul_f32_e32 v116, v43, v43
	v_pk_fma_f32 v[38:39], v[58:59], v[58:59], v[38:39] op_sel_hi:[1,1,0]
	v_pk_fma_f32 v[48:49], v[60:61], v[60:61], v[48:49] op_sel_hi:[1,1,0]
	v_lshlrev_b32_e32 v32, 16, v34
	v_and_b32_e32 v33, 0xffff0000, v34
	v_lshlrev_b32_e32 v34, 16, v35
	v_and_b32_e32 v35, 0xffff0000, v35
	v_mov_b32_e32 v39, v115
	v_mov_b32_e32 v49, v116
	v_pk_add_f32 v[38:39], v[38:39], v[48:49]
	v_mul_f32_e32 v48, v33, v33
	v_mul_f32_e32 v50, v35, v35
	v_mul_f32_e32 v117, v40, v40
	v_mul_f32_e32 v118, v41, v41
	v_pk_fma_f32 v[48:49], v[32:33], v[32:33], v[48:49] op_sel_hi:[1,1,0]
	v_pk_fma_f32 v[50:51], v[34:35], v[34:35], v[50:51] op_sel_hi:[1,1,0]
	v_mov_b32_e32 v49, v117
	v_mov_b32_e32 v51, v118
	v_pk_add_f32 v[48:49], v[48:49], v[50:51]
	v_mov_b32_e32 v54, v66
	v_pk_add_f32 v[38:39], v[38:39], v[48:49]
	v_mov_b32_e32 v55, v68
	v_pk_add_f32 v[36:37], v[36:37], v[38:39]
	v_mov_b32_e32 v68, v67
	v_add_f32_e32 v36, v36, v37
	ds_bpermute_b32 v37, v169, v36
	s_waitcnt lgkmcnt(0)
; __device__ __forceinline__ u32x4 pack8(f32x4 a, f32x4 b) { u32x4 o; o.x = cvt_pk(a.x, a.y); o.y = cvt_pk(a.z, a.w); o.z = cvt_pk(b.x, b.y); o.w = cvt_pk(b.z, b.w); return o; }
; #define LBAR() do { asm volatile("s_waitcnt lgkmcnt(0)" ::: "memory"); __builtin_amdgcn_s_barrier(); asm volatile("" ::: "memory"); } while (0)
; __device__ __forceinline__ void attn_phase(const Params& p, LAS unsigned char* lds, int G) {
;     ...
;             const float r = QSCALE / sqrtf(ss * (1.f / 96.f) + EPS);
; #pragma unroll
;             for (int ks = 0; ks < 6; ++ks) { const f32x4 ga = *(const f32x4*)(p.in[15] + 16 * ks + 8 * hi), gb = *(const f32x4*)(p.in[15] + 16 * ks + 8 * hi + 4);
;                 xa[ks] = xa[ks] * ga * r; xb[ks] = xb[ks] * gb * r; }
;             const f32x4 ra = xa[4] * c0 - xa[5] * n0, rb = xb[4] * c1 - xb[5] * n1, rc = xa[5] * c0 + xa[4] * n0, rd = xb[5] * c1 + xb[4] * n1;
;             xa[4] = ra; xb[4] = rb; xa[5] = rc; xb[5] = rd;
; #pragma unroll
;             for (int ks = 0; ks < 6; ++ks) qf[ks] = __builtin_bit_cast(bf16x8, pack8(xa[ks], xb[ks]));
;         }
;         f32x16 o0, o1;
; #pragma unroll
;         for (int e = 0; e < 16; ++e) { o0[e] = 0.f; o1[e] = 0.f; }
;         float lsum = 0.f;
;         const int nst = nkt >> 1;
;         ATT_STORE(0);
;         LBAR();
	v_add_f32_e32 v36, v36, v37
	v_fmamk_f32 v36, v36, 0x3c2aaaab, v182
	v_cmp_gt_f32_e32 vcc, s0, v36
	v_mul_f32_e32 v37, 0x4f800000, v36
	s_nop 0
	v_cndmask_b32_e32 v36, v36, v37, vcc
	v_sqrt_f32_e32 v37, v36
	s_nop 0
	v_add_u32_e32 v38, -1, v37
	v_fma_f32 v39, -v38, v37, v36
	v_cmp_ge_f32_e64 s[0:1], 0, v39
	v_add_u32_e32 v39, 1, v37
	s_nop 0
	v_cndmask_b32_e64 v38, v37, v38, s[0:1]
	v_fma_f32 v37, -v39, v37, v36
	v_cmp_lt_f32_e64 s[0:1], 0, v37
	s_nop 1
	v_cndmask_b32_e64 v37, v38, v39, s[0:1]
	v_mul_f32_e32 v38, 0x37800000, v37
	v_cndmask_b32_e32 v37, v37, v38, vcc
	v_cmp_class_f32_e32 vcc, v36, v183
	s_nop 1
	v_cndmask_b32_e32 v36, v37, v36, vcc
	v_div_scale_f32 v37, s[0:1], v36, v36, s11
	v_rcp_f32_e32 v38, v37
	s_nop 0
	v_fma_f32 v39, -v37, v38, 1.0
	v_fmac_f32_e32 v38, v39, v38
	v_div_scale_f32 v39, vcc, s11, v36, s11
	v_mul_f32_e32 v48, v39, v38
	v_fma_f32 v49, -v37, v48, v39
	v_fmac_f32_e32 v48, v49, v38
	v_fma_f32 v37, -v37, v48, v39
	v_div_fmas_f32 v37, v37, v38, v48
	v_div_fixup_f32 v48, v37, v36, s11
	global_load_dwordx4 v[36:39], v[146:147], off offset:16
	global_load_dwordx4 v[50:53], v[146:147], off
	s_waitcnt vmcnt(0)
	v_pk_mul_f32 v[54:55], v[54:55], v[50:51]
	v_mov_b32_e32 v50, v70
	v_mov_b32_e32 v51, v72
	v_pk_mul_f32 v[50:51], v[50:51], v[52:53]
	v_mov_b32_e32 v52, v106
	v_mov_b32_e32 v53, v108
	v_pk_mul_f32 v[36:37], v[52:53], v[36:37]
	v_mov_b32_e32 v52, v110
	v_mov_b32_e32 v53, v112
	v_pk_mul_f32 v[38:39], v[52:53], v[38:39]
	v_pk_mul_f32 v[56:57], v[36:37], v[48:49] op_sel_hi:[1,0]
	v_pk_mul_f32 v[52:53], v[38:39], v[48:49] op_sel_hi:[1,0]
	global_load_dwordx4 v[36:39], v[146:147], off offset:80
	global_load_dwordx4 v[114:117], v[146:147], off offset:64
	v_mov_b32_e32 v108, v107
	v_mov_b32_e32 v112, v111
	v_mov_b32_e32 v72, v71
	v_mov_b32_e32 v110, v78
	v_mov_b32_e32 v111, v100
	v_mov_b32_e32 v100, v79
	v_pk_mul_f32 v[50:51], v[50:51], v[48:49] op_sel_hi:[1,0]
	v_pk_mul_f32 v[54:55], v[54:55], v[48:49] op_sel_hi:[1,0]
	s_waitcnt vmcnt(1)
	v_pk_mul_f32 v[36:37], v[108:109], v[36:37]
	s_waitcnt vmcnt(0)
	v_pk_mul_f32 v[68:69], v[68:69], v[114:115]
	v_pk_mul_f32 v[38:39], v[112:113], v[38:39]
	v_pk_mul_f32 v[66:67], v[72:73], v[116:117]
	v_pk_mul_f32 v[70:71], v[68:69], v[48:49] op_sel_hi:[1,0]
	v_pk_mul_f32 v[68:69], v[38:39], v[48:49] op_sel_hi:[1,0]
	v_pk_mul_f32 v[72:73], v[36:37], v[48:49] op_sel_hi:[1,0]
	global_load_dwordx4 v[36:39], v[146:147], off offset:144
	global_load_dwordx4 v[106:109], v[146:147], off offset:128
	v_pk_mul_f32 v[66:67], v[66:67], v[48:49] op_sel_hi:[1,0]
	s_waitcnt vmcnt(1)
	v_pk_mul_f32 v[36:37], v[100:101], v[36:37]
	s_waitcnt vmcnt(0)
	v_pk_mul_f32 v[106:107], v[110:111], v[106:107]
	v_mov_b32_e32 v111, v104
	v_mov_b32_e32 v104, v103
	v_pk_mul_f32 v[38:39], v[104:105], v[38:39]
	v_mov_b32_e32 v110, v102
	v_pk_mul_f32 v[78:79], v[38:39], v[48:49] op_sel_hi:[1,0]
	v_pk_mul_f32 v[112:113], v[36:37], v[48:49] op_sel_hi:[1,0]
	global_load_dwordx4 v[36:39], v[146:147], off offset:208
	global_load_dwordx4 v[100:103], v[146:147], off offset:192
	v_mov_b32_e32 v105, v64
	v_mov_b32_e32 v64, v63
	v_mov_b32_e32 v104, v62
	v_pk_mul_f32 v[108:109], v[110:111], v[108:109]
	s_waitcnt vmcnt(0)
	v_pk_mul_f32 v[62:63], v[102:103], v[64:65]
	v_mov_b32_e32 v64, v74
	v_mov_b32_e32 v65, v76
	v_mov_b32_e32 v76, v75
	v_pk_mul_f32 v[100:101], v[100:101], v[104:105]
	v_pk_mul_f32 v[36:37], v[36:37], v[64:65]
	v_pk_mul_f32 v[38:39], v[38:39], v[76:77]
	v_pk_mul_f32 v[114:115], v[100:101], v[48:49] op_sel_hi:[1,0]
	v_pk_mul_f32 v[64:65], v[38:39], v[48:49] op_sel_hi:[1,0]
	v_pk_mul_f32 v[74:75], v[36:37], v[48:49] op_sel_hi:[1,0]
	global_load_dwordx4 v[36:39], v[146:147], off offset:272
	global_load_dwordx4 v[100:103], v[146:147], off offset:256
	v_pk_mul_f32 v[110:111], v[108:109], v[48:49] op_sel_hi:[1,0]
	v_pk_mul_f32 v[108:109], v[106:107], v[48:49] op_sel_hi:[1,0]
	v_pk_mul_f32 v[62:63], v[62:63], v[48:49] op_sel_hi:[1,0]
	s_waitcnt vmcnt(1)
	v_pk_mul_f32 v[34:35], v[38:39], v[34:35]
	s_waitcnt vmcnt(0)
	v_pk_mul_f32 v[60:61], v[102:103], v[60:61]
	v_pk_mul_f32 v[32:33], v[36:37], v[32:33]
	v_pk_mul_f32 v[58:59], v[100:101], v[58:59]
	v_pk_mul_f32 v[76:77], v[48:49], v[60:61] op_sel_hi:[0,1]
	v_pk_mul_f32 v[60:61], v[48:49], v[32:33] op_sel_hi:[0,1]
	v_pk_mul_f32 v[100:101], v[48:49], v[34:35] op_sel_hi:[0,1]
	global_load_dwordx4 v[32:35], v[146:147], off offset:336
	global_load_dwordx4 v[36:39], v[146:147], off offset:320
	v_pk_mul_f32 v[58:59], v[48:49], v[58:59] op_sel_hi:[0,1]
	s_waitcnt vmcnt(1)
	v_pk_mul_f32 v[32:33], v[42:43], v[32:33]
	s_waitcnt vmcnt(0)
	v_pk_mul_f32 v[36:37], v[46:47], v[36:37]
	v_pk_mul_f32 v[38:39], v[44:45], v[38:39]
	v_pk_mul_f32 v[34:35], v[40:41], v[34:35]
	v_pk_mul_f32 v[32:33], v[48:49], v[32:33] op_sel_hi:[0,1]
	v_pk_mul_f32 v[38:39], v[48:49], v[38:39] op_sel_hi:[0,1]
	v_pk_mul_f32 v[36:37], v[48:49], v[36:37] op_sel_hi:[0,1]
	v_pk_mul_f32 v[34:35], v[48:49], v[34:35] op_sel_hi:[0,1]
	v_pk_mul_f32 v[44:45], v[20:21], v[32:33]
	v_pk_mul_f32 v[40:41], v[28:29], v[36:37]
	v_pk_mul_f32 v[42:43], v[30:31], v[38:39]
	v_pk_mul_f32 v[46:47], v[22:23], v[34:35]
	v_pk_fma_f32 v[44:45], v[16:17], v[60:61], v[44:45] neg_lo:[0,0,1] neg_hi:[0,0,1]
	v_pk_mul_f32 v[16:17], v[16:17], v[32:33]
	v_pk_fma_f32 v[42:43], v[26:27], v[76:77], v[42:43] neg_lo:[0,0,1] neg_hi:[0,0,1]
	v_pk_fma_f32 v[40:41], v[24:25], v[58:59], v[40:41] neg_lo:[0,0,1] neg_hi:[0,0,1]
	v_pk_fma_f32 v[46:47], v[18:19], v[100:101], v[46:47] neg_lo:[0,0,1] neg_hi:[0,0,1]
	v_pk_mul_f32 v[24:25], v[24:25], v[36:37]
	v_pk_mul_f32 v[26:27], v[26:27], v[38:39]
	v_pk_mul_f32 v[18:19], v[18:19], v[34:35]
	v_pk_fma_f32 v[16:17], v[20:21], v[60:61], v[16:17]
	v_pk_fma_f32 v[26:27], v[30:31], v[76:77], v[26:27]
	v_pk_fma_f32 v[24:25], v[28:29], v[58:59], v[24:25]
	v_pk_fma_f32 v[18:19], v[22:23], v[100:101], v[18:19]
	v_cvt_pk_bf16_f32 v100, v54, v55
	v_cvt_pk_bf16_f32 v101, v50, v51
	v_cvt_pk_bf16_f32 v102, v56, v57
	v_cvt_pk_bf16_f32 v103, v52, v53
	v_cvt_pk_bf16_f32 v104, v70, v71
	v_cvt_pk_bf16_f32 v105, v66, v67
	v_cvt_pk_bf16_f32 v106, v72, v73
	v_cvt_pk_bf16_f32 v107, v68, v69
	v_cvt_pk_bf16_f32 v108, v108, v109
	v_cvt_pk_bf16_f32 v109, v110, v111
	v_cvt_pk_bf16_f32 v110, v112, v113
	v_cvt_pk_bf16_f32 v111, v78, v79
	v_cvt_pk_bf16_f32 v112, v114, v115
	v_cvt_pk_bf16_f32 v113, v62, v63
	v_cvt_pk_bf16_f32 v114, v74, v75
	v_cvt_pk_bf16_f32 v115, v64, v65
	v_cvt_pk_bf16_f32 v116, v40, v41
	v_cvt_pk_bf16_f32 v117, v42, v43
	v_cvt_pk_bf16_f32 v118, v44, v45
	v_cvt_pk_bf16_f32 v119, v46, v47
	v_cvt_pk_bf16_f32 v120, v24, v25
	v_cvt_pk_bf16_f32 v121, v26, v27
	v_cvt_pk_bf16_f32 v122, v16, v17
	v_add_u32_e32 v16, 0xd000, v250
	v_cvt_pk_bf16_f32 v123, v18, v19
	ds_write_b128 v184, v[80:83]
	ds_write_b128 v185, v[84:87]
	ds_write_b128 v186, v[88:91]
	ds_write2_b64 v16, v[92:93], v[94:95] offset1:2
	v_add_u32_e32 v16, 0xf200, v250
	ds_write2_b64 v16, v[96:97], v[98:99] offset1:2
	s_waitcnt lgkmcnt(0)
	s_barrier
; #define LBAR() do { asm volatile("s_waitcnt lgkmcnt(0)" ::: "memory"); __builtin_amdgcn_s_barrier(); asm volatile("" ::: "memory"); } while (0)
; __device__ __forceinline__ void attn_phase(const Params& p, LAS unsigned char* lds, int G) {
;     ...
;         f32x16 o0, o1;
; #pragma unroll
;         for (int e = 0; e < 16; ++e) { o0[e] = 0.f; o1[e] = 0.f; }
;         float lsum = 0.f;
;         const int nst = nkt >> 1;
;         ATT_STORE(0);
;         LBAR();
;         for (int st = 0; st < nst; ++st) {
;             const int buf = st & 1; const bool more = (st + 1 < nst);
;             if (more) ATT_LOAD(st + 1);
;             if (2 * st <= lim) ATT_COMPUTE(buf, 0);
;             if (2 * st + 1 <= lim) ATT_COMPUTE(buf, 1);
;             if (more) ATT_STORE(buf ^ 1);
;             LBAR();
	v_mov_b32_e32 v30, v125
	v_mov_b32_e32 v31, v125
	v_mov_b32_e32 v16, v125
	v_mov_b32_e32 v17, v125
	v_mov_b32_e32 v18, v125
	v_mov_b32_e32 v19, v125
	v_mov_b32_e32 v20, v125
	v_mov_b32_e32 v21, v125
	v_mov_b32_e32 v22, v125
	v_mov_b32_e32 v23, v125
	v_mov_b32_e32 v24, v125
	v_mov_b32_e32 v25, v125
	v_mov_b32_e32 v26, v125
	v_mov_b32_e32 v27, v125
	v_mov_b32_e32 v28, v125
	v_mov_b32_e32 v29, v125
	v_mov_b64_e32 v[46:47], v[30:31]
	v_mov_b64_e32 v[44:45], v[28:29]
	v_mov_b64_e32 v[42:43], v[26:27]
	v_mov_b64_e32 v[40:41], v[24:25]
	v_mov_b64_e32 v[38:39], v[22:23]
	v_mov_b64_e32 v[36:37], v[20:21]
	v_mov_b64_e32 v[34:35], v[18:19]
	v_mov_b64_e32 v[32:33], v[16:17]
	s_mov_b32 s48, 0
	s_lshl_b32 s49, s47, 1
	s_add_u32 s49, s49, 1
	s_mov_b32 s16, 0
	s_mov_b32 s17, 0x15800
	s_mov_b32 s18, 0xd000
	s_mov_b32 s19, 0x11400
	ds_read_b128 v[190:193], v179 offset:0
	ds_read_b128 v[194:197], v179 offset:32
	ds_read_b128 v[198:201], v179 offset:64
	ds_read_b128 v[202:205], v179 offset:96
	ds_read_b128 v[206:209], v179 offset:128
	ds_read_b128 v[210:213], v179 offset:160
	v_mov_b32_e32 v238, 0
	v_mov_b32_e32 v239, 0
	v_mov_b32_e32 v240, 0
	v_mov_b32_e32 v241, 0
	v_add_u32_e32 v243, s18, v249
	s_waitcnt lgkmcnt(0)
	v_mfma_f32_32x32x16_bf16 v[48:63], v[190:193], v[100:103], v[0:15]
	v_mfma_f32_32x32x16_bf16 v[48:63], v[194:197], v[104:107], v[48:63]
	v_mfma_f32_32x32x16_bf16 v[48:63], v[198:201], v[108:111], v[48:63]
	v_mfma_f32_32x32x16_bf16 v[48:63], v[202:205], v[112:115], v[48:63]
	v_mfma_f32_32x32x16_bf16 v[48:63], v[206:209], v[116:119], v[48:63]
	v_mfma_f32_32x32x16_bf16 v[48:63], v[210:213], v[120:123], v[48:63]
	ds_read_b128 v[190:193], v179 offset:6656
	ds_read_b128 v[194:197], v179 offset:6688
	ds_read_b128 v[198:201], v179 offset:6720
	ds_read_b128 v[202:205], v179 offset:6752
	ds_read_b128 v[206:209], v179 offset:6784
	ds_read_b128 v[210:213], v179 offset:6816
	ds_read_b128 v[214:217], v243 offset:0
	ds_read_b128 v[218:221], v243 offset:8704
	ds_read_b128 v[222:225], v243 offset:32
	ds_read_b128 v[226:229], v243 offset:8736
	s_nop 7
.Latt_iter:
	s_add_u32 s15, s48, 1
	s_cmp_lt_u32 s15, s14
	s_cbranch_scc0 .Latt_noload
	s_lshl_b64 s[0:1], s[30:31], 1
	s_add_u32 s0, s42, s0
	s_addc_u32 s1, s43, s1
	global_load_dwordx4 v[80:83], v[160:161], off
	global_load_dwordx4 v[84:87], v[162:163], off
	global_load_dwordx4 v[88:91], v[164:165], off
	v_lshl_add_u64 v[252:253], v[138:139], 1, s[0:1]
	v_lshl_add_u64 v[252:253], v[252:253], 0, v[124:125]
	global_load_dwordx4 v[92:95], v[252:253], off
	v_lshl_add_u64 v[252:253], v[140:141], 1, s[0:1]
	v_lshl_add_u64 v[252:253], v[252:253], 0, v[124:125]
	global_load_dwordx4 v[96:99], v[252:253], off
.Latt_noload:
	v_add_u32_e32 v242, s16, v179
	v_add_u32_e32 v243, s18, v249
	v_add_u32_e32 v244, s17, v249
	s_cmp_eq_u32 s48, 0
	s_cbranch_scc1 .Latt_skipA
	s_lshl_b32 s15, s48, 2
	s_sub_u32 s15, s15, 1
	s_cmp_le_u32 s15, s49
	s_cbranch_scc0 .Latt_skipA
	s_waitcnt lgkmcnt(7)
	v_mfma_f32_32x32x16_bf16 v[64:79], v[190:193], v[100:103], v[0:15]
	v_exp_f32_e32 v48, v48
	v_exp_f32_e32 v49, v49
	v_exp_f32_e32 v50, v50
	v_mfma_f32_32x32x16_bf16 v[64:79], v[194:197], v[104:107], v[64:79]
	v_exp_f32_e32 v51, v51
	v_exp_f32_e32 v52, v52
	v_exp_f32_e32 v53, v53
	v_mfma_f32_32x32x16_bf16 v[64:79], v[198:201], v[108:111], v[64:79]
	ds_read_b128 v[190:193], v242 offset:0
	ds_read_b128 v[194:197], v242 offset:32
	ds_read_b128 v[198:201], v242 offset:64
	v_exp_f32_e32 v54, v54
	v_exp_f32_e32 v55, v55
	v_cvt_pk_bf16_f32 v230, v48, v49
	v_cvt_pk_bf16_f32 v231, v50, v51
	s_waitcnt lgkmcnt(7)
	v_mfma_f32_32x32x16_bf16 v[64:79], v[202:205], v[112:115], v[64:79]
	v_cvt_pk_bf16_f32 v232, v52, v53
	v_cvt_pk_bf16_f32 v233, v54, v55
	v_exp_f32_e32 v56, v56
	v_exp_f32_e32 v57, v57
	v_mfma_f32_32x32x16_bf16 v[64:79], v[206:209], v[116:119], v[64:79]
	v_exp_f32_e32 v58, v58
	v_exp_f32_e32 v59, v59
	v_exp_f32_e32 v60, v60
	v_mfma_f32_32x32x16_bf16 v[64:79], v[210:213], v[120:123], v[64:79]
	ds_read_b128 v[202:205], v242 offset:96
	ds_read_b128 v[206:209], v242 offset:128
	ds_read_b128 v[210:213], v242 offset:160
	v_exp_f32_e32 v61, v61
	v_exp_f32_e32 v62, v62
	v_exp_f32_e32 v63, v63
	s_waitcnt lgkmcnt(6)
	v_mfma_f32_32x32x16_bf16 v[16:31], v[214:217], v[230:233], v[16:31]
	v_cvt_pk_bf16_f32 v234, v56, v57
	v_cvt_pk_bf16_f32 v235, v58, v59
	v_cvt_pk_bf16_f32 v236, v60, v61
	v_cvt_pk_bf16_f32 v237, v62, v63
	v_add_f32_e32 v238, v238, v48
	v_add_f32_e32 v239, v239, v49
	v_mfma_f32_32x32x16_bf16 v[32:47], v[218:221], v[230:233], v[32:47]
	v_add_f32_e32 v240, v240, v50
	v_add_f32_e32 v241, v241, v51
	v_add_f32_e32 v238, v238, v52
	v_add_f32_e32 v239, v239, v53
	v_add_f32_e32 v240, v240, v54
	v_add_f32_e32 v241, v241, v55
	v_mfma_f32_32x32x16_bf16 v[16:31], v[222:225], v[234:237], v[16:31]
	v_add_f32_e32 v238, v238, v56
	v_add_f32_e32 v239, v239, v57
	v_add_f32_e32 v240, v240, v58
	v_add_f32_e32 v241, v241, v59
	v_add_f32_e32 v238, v238, v60
	v_add_f32_e32 v239, v239, v61
	v_mfma_f32_32x32x16_bf16 v[32:47], v[226:229], v[234:237], v[32:47]
	ds_read_b128 v[214:217], v244 offset:192
	ds_read_b128 v[218:221], v244 offset:8896
	ds_read_b128 v[222:225], v244 offset:224
	ds_read_b128 v[226:229], v244 offset:8928
	v_add_f32_e32 v240, v240, v62
	v_add_f32_e32 v241, v241, v63
	s_waitcnt lgkmcnt(7)
	v_mfma_f32_32x32x16_bf16 v[48:63], v[190:193], v[100:103], v[0:15]
	v_exp_f32_e32 v64, v64
	v_exp_f32_e32 v65, v65
	v_exp_f32_e32 v66, v66
	v_mfma_f32_32x32x16_bf16 v[48:63], v[194:197], v[104:107], v[48:63]
	v_exp_f32_e32 v67, v67
	v_exp_f32_e32 v68, v68
	v_exp_f32_e32 v69, v69
	v_mfma_f32_32x32x16_bf16 v[48:63], v[198:201], v[108:111], v[48:63]
	ds_read_b128 v[190:193], v242 offset:6656
	ds_read_b128 v[194:197], v242 offset:6688
	ds_read_b128 v[198:201], v242 offset:6720
	v_exp_f32_e32 v70, v70
	v_exp_f32_e32 v71, v71
	v_cvt_pk_bf16_f32 v230, v64, v65
	v_cvt_pk_bf16_f32 v231, v66, v67
	s_waitcnt lgkmcnt(7)
	v_mfma_f32_32x32x16_bf16 v[48:63], v[202:205], v[112:115], v[48:63]
	v_cvt_pk_bf16_f32 v232, v68, v69
	v_cvt_pk_bf16_f32 v233, v70, v71
	v_exp_f32_e32 v72, v72
	v_exp_f32_e32 v73, v73
	v_mfma_f32_32x32x16_bf16 v[48:63], v[206:209], v[116:119], v[48:63]
	v_exp_f32_e32 v74, v74
	v_exp_f32_e32 v75, v75
	v_exp_f32_e32 v76, v76
	v_mfma_f32_32x32x16_bf16 v[48:63], v[210:213], v[120:123], v[48:63]
	ds_read_b128 v[202:205], v242 offset:6752
	ds_read_b128 v[206:209], v242 offset:6784
	ds_read_b128 v[210:213], v242 offset:6816
	v_exp_f32_e32 v77, v77
	v_exp_f32_e32 v78, v78
	v_exp_f32_e32 v79, v79
	s_waitcnt lgkmcnt(6)
	v_mfma_f32_32x32x16_bf16 v[16:31], v[214:217], v[230:233], v[16:31]
	v_cvt_pk_bf16_f32 v234, v72, v73
	v_cvt_pk_bf16_f32 v235, v74, v75
	v_cvt_pk_bf16_f32 v236, v76, v77
	v_cvt_pk_bf16_f32 v237, v78, v79
	v_add_f32_e32 v238, v238, v64
	v_add_f32_e32 v239, v239, v65
	v_mfma_f32_32x32x16_bf16 v[32:47], v[218:221], v[230:233], v[32:47]
	v_add_f32_e32 v240, v240, v66
	v_add_f32_e32 v241, v241, v67
	v_add_f32_e32 v238, v238, v68
	v_add_f32_e32 v239, v239, v69
	v_add_f32_e32 v240, v240, v70
	v_add_f32_e32 v241, v241, v71
	v_mfma_f32_32x32x16_bf16 v[16:31], v[222:225], v[234:237], v[16:31]
	v_add_f32_e32 v238, v238, v72
	v_add_f32_e32 v239, v239, v73
	v_add_f32_e32 v240, v240, v74
	v_add_f32_e32 v241, v241, v75
	v_add_f32_e32 v238, v238, v76
	v_add_f32_e32 v239, v239, v77
	v_mfma_f32_32x32x16_bf16 v[32:47], v[226:229], v[234:237], v[32:47]
	ds_read_b128 v[214:217], v243 offset:0
	ds_read_b128 v[218:221], v243 offset:8704
	ds_read_b128 v[222:225], v243 offset:32
	ds_read_b128 v[226:229], v243 offset:8736
	v_add_f32_e32 v240, v240, v78
	v_add_f32_e32 v241, v241, v79
; #define LBAR() do { asm volatile("s_waitcnt lgkmcnt(0)" ::: "memory"); __builtin_amdgcn_s_barrier(); asm volatile("" ::: "memory"); } while (0)
; __device__ __forceinline__ void attn_phase(const Params& p, LAS unsigned char* lds, int G) {
;     ...
;         for (int st = 0; st < nst; ++st) {
;             const int buf = st & 1; const bool more = (st + 1 < nst);
;             if (more) ATT_LOAD(st + 1);
;             if (2 * st <= lim) ATT_COMPUTE(buf, 0);
;             if (2 * st + 1 <= lim) ATT_COMPUTE(buf, 1);
;             if (more) ATT_STORE(buf ^ 1);
;             LBAR();
;         }
;         lsum += __shfl_xor(lsum, 32);
;         const float inv = 1.0f / lsum;
.Latt_skipA:
	s_lshl_b32 s15, s48, 2
	s_add_u32 s15, s15, 1
	s_cmp_le_u32 s15, s49
	s_cbranch_scc0 .Latt_skipB
	s_waitcnt lgkmcnt(7)
	v_mfma_f32_32x32x16_bf16 v[64:79], v[190:193], v[100:103], v[0:15]
	v_exp_f32_e32 v48, v48
	v_exp_f32_e32 v49, v49
	v_exp_f32_e32 v50, v50
	v_mfma_f32_32x32x16_bf16 v[64:79], v[194:197], v[104:107], v[64:79]
	v_exp_f32_e32 v51, v51
	v_exp_f32_e32 v52, v52
	v_exp_f32_e32 v53, v53
	v_mfma_f32_32x32x16_bf16 v[64:79], v[198:201], v[108:111], v[64:79]
	ds_read_b128 v[190:193], v242 offset:13312
	ds_read_b128 v[194:197], v242 offset:13344
	ds_read_b128 v[198:201], v242 offset:13376
	v_exp_f32_e32 v54, v54
	v_exp_f32_e32 v55, v55
	v_cvt_pk_bf16_f32 v230, v48, v49
	v_cvt_pk_bf16_f32 v231, v50, v51
	s_waitcnt lgkmcnt(7)
	v_mfma_f32_32x32x16_bf16 v[64:79], v[202:205], v[112:115], v[64:79]
	v_cvt_pk_bf16_f32 v232, v52, v53
	v_cvt_pk_bf16_f32 v233, v54, v55
	v_exp_f32_e32 v56, v56
	v_exp_f32_e32 v57, v57
	v_mfma_f32_32x32x16_bf16 v[64:79], v[206:209], v[116:119], v[64:79]
	v_exp_f32_e32 v58, v58
	v_exp_f32_e32 v59, v59
	v_exp_f32_e32 v60, v60
	v_mfma_f32_32x32x16_bf16 v[64:79], v[210:213], v[120:123], v[64:79]
	ds_read_b128 v[202:205], v242 offset:13408
	ds_read_b128 v[206:209], v242 offset:13440
	ds_read_b128 v[210:213], v242 offset:13472
	v_exp_f32_e32 v61, v61
	v_exp_f32_e32 v62, v62
	v_exp_f32_e32 v63, v63
	s_waitcnt lgkmcnt(6)
	v_mfma_f32_32x32x16_bf16 v[16:31], v[214:217], v[230:233], v[16:31]
	v_cvt_pk_bf16_f32 v234, v56, v57
	v_cvt_pk_bf16_f32 v235, v58, v59
	v_cvt_pk_bf16_f32 v236, v60, v61
	v_cvt_pk_bf16_f32 v237, v62, v63
	v_add_f32_e32 v238, v238, v48
	v_add_f32_e32 v239, v239, v49
	v_mfma_f32_32x32x16_bf16 v[32:47], v[218:221], v[230:233], v[32:47]
	v_add_f32_e32 v240, v240, v50
	v_add_f32_e32 v241, v241, v51
	v_add_f32_e32 v238, v238, v52
	v_add_f32_e32 v239, v239, v53
	v_add_f32_e32 v240, v240, v54
	v_add_f32_e32 v241, v241, v55
	v_mfma_f32_32x32x16_bf16 v[16:31], v[222:225], v[234:237], v[16:31]
	v_add_f32_e32 v238, v238, v56
	v_add_f32_e32 v239, v239, v57
	v_add_f32_e32 v240, v240, v58
	v_add_f32_e32 v241, v241, v59
	v_add_f32_e32 v238, v238, v60
	v_add_f32_e32 v239, v239, v61
	v_mfma_f32_32x32x16_bf16 v[32:47], v[226:229], v[234:237], v[32:47]
	ds_read_b128 v[214:217], v243 offset:64
	ds_read_b128 v[218:221], v243 offset:8768
	ds_read_b128 v[222:225], v243 offset:96
	ds_read_b128 v[226:229], v243 offset:8800
	v_add_f32_e32 v240, v240, v62
	v_add_f32_e32 v241, v241, v63
	s_waitcnt lgkmcnt(7)
	v_mfma_f32_32x32x16_bf16 v[48:63], v[190:193], v[100:103], v[0:15]
	v_exp_f32_e32 v64, v64
	v_exp_f32_e32 v65, v65
	v_exp_f32_e32 v66, v66
	v_mfma_f32_32x32x16_bf16 v[48:63], v[194:197], v[104:107], v[48:63]
	v_exp_f32_e32 v67, v67
	v_exp_f32_e32 v68, v68
	v_exp_f32_e32 v69, v69
	v_mfma_f32_32x32x16_bf16 v[48:63], v[198:201], v[108:111], v[48:63]
	ds_read_b128 v[190:193], v242 offset:19968
	ds_read_b128 v[194:197], v242 offset:20000
	ds_read_b128 v[198:201], v242 offset:20032
	v_exp_f32_e32 v70, v70
	v_exp_f32_e32 v71, v71
	v_cvt_pk_bf16_f32 v230, v64, v65
	v_cvt_pk_bf16_f32 v231, v66, v67
	s_waitcnt lgkmcnt(7)
	v_mfma_f32_32x32x16_bf16 v[48:63], v[202:205], v[112:115], v[48:63]
	v_cvt_pk_bf16_f32 v232, v68, v69
	v_cvt_pk_bf16_f32 v233, v70, v71
	v_exp_f32_e32 v72, v72
	v_exp_f32_e32 v73, v73
	v_mfma_f32_32x32x16_bf16 v[48:63], v[206:209], v[116:119], v[48:63]
	v_exp_f32_e32 v74, v74
	v_exp_f32_e32 v75, v75
	v_exp_f32_e32 v76, v76
	v_mfma_f32_32x32x16_bf16 v[48:63], v[210:213], v[120:123], v[48:63]
	ds_read_b128 v[202:205], v242 offset:20064
	ds_read_b128 v[206:209], v242 offset:20096
	ds_read_b128 v[210:213], v242 offset:20128
	v_exp_f32_e32 v77, v77
	v_exp_f32_e32 v78, v78
	v_exp_f32_e32 v79, v79
	s_waitcnt lgkmcnt(6)
	v_mfma_f32_32x32x16_bf16 v[16:31], v[214:217], v[230:233], v[16:31]
	v_cvt_pk_bf16_f32 v234, v72, v73
	v_cvt_pk_bf16_f32 v235, v74, v75
	v_cvt_pk_bf16_f32 v236, v76, v77
	v_cvt_pk_bf16_f32 v237, v78, v79
	v_add_f32_e32 v238, v238, v64
	v_add_f32_e32 v239, v239, v65
	v_mfma_f32_32x32x16_bf16 v[32:47], v[218:221], v[230:233], v[32:47]
	v_add_f32_e32 v240, v240, v66
	v_add_f32_e32 v241, v241, v67
	v_add_f32_e32 v238, v238, v68
	v_add_f32_e32 v239, v239, v69
	v_add_f32_e32 v240, v240, v70
	v_add_f32_e32 v241, v241, v71
	v_mfma_f32_32x32x16_bf16 v[16:31], v[222:225], v[234:237], v[16:31]
	v_add_f32_e32 v238, v238, v72
	v_add_f32_e32 v239, v239, v73
	v_add_f32_e32 v240, v240, v74
	v_add_f32_e32 v241, v241, v75
	v_add_f32_e32 v238, v238, v76
	v_add_f32_e32 v239, v239, v77
	v_mfma_f32_32x32x16_bf16 v[32:47], v[226:229], v[234:237], v[32:47]
	ds_read_b128 v[214:217], v243 offset:128
	ds_read_b128 v[218:221], v243 offset:8832
	ds_read_b128 v[222:225], v243 offset:160
	ds_read_b128 v[226:229], v243 offset:8864
	v_add_f32_e32 v240, v240, v78
	v_add_f32_e32 v241, v241, v79
.Latt_skipB:
	s_add_u32 s15, s48, 1
	s_cmp_lt_u32 s15, s14
	s_cbranch_scc0 .Latt_nostore
	s_xor_b32 s0, s16, 0x6800
	s_waitcnt vmcnt(0)
	v_add_u32_e32 v245, s0, v184
	ds_write_b128 v245, v[80:83]
	v_add_u32_e32 v245, s0, v185
	ds_write_b128 v245, v[84:87]
	v_add_u32_e32 v245, s0, v186
	ds_write_b128 v245, v[88:91]
	v_add_u32_e32 v245, s19, v250
	ds_write2_b64 v245, v[92:93], v[94:95] offset1:2
	v_add_u32_e32 v246, 0x2200, v245
	ds_write2_b64 v246, v[96:97], v[98:99] offset1:2
	s_addk_i32 s30, 0x80
	v_lshl_add_u64 v[160:161], v[160:161], 0, s[36:37]
	v_lshl_add_u64 v[162:163], v[162:163], 0, s[36:37]
	v_lshl_add_u64 v[164:165], v[164:165], 0, s[36:37]
.Latt_nostore:
	s_waitcnt lgkmcnt(0)
	s_barrier
	s_xor_b32 s16, s16, 0x6800
	s_mov_b32 s0, s17
	s_mov_b32 s17, s18
	s_mov_b32 s18, s19
	s_mov_b32 s19, s0
	s_add_u32 s48, s48, 1
	s_cmp_le_u32 s48, s14
	s_cbranch_scc1 .Latt_iter
	s_nop 7
	v_add_f32_e32 v238, v238, v239
	v_add_f32_e32 v240, v240, v241
	v_add_f32_e32 v155, v238, v240
	s_nop 7
